# speedup vs baseline: 1.0014x; 1.0014x over previous
; __device__ void peer_phase(const Params& p) {
;     ...
;     for (int hf = 0; hf < 2; ++hf) {
;       int acti = 0;
;       for (int e = 0; e < 64; e += 16) {
;         uint4 d[16];
; #pragma unroll
;         for (int u = 0; u < 16; ++u) {
;           const int id = __builtin_amdgcn_readlane(eid[hf], e + u);
;           d[u] = ((const uint4*)(down4 + (size_t)id * 1024))[lane];
;         }
; #pragma unroll
;         for (int u = 0; u < 16; ++u) {
;           const u32 w[4] = {d[u].x, d[u].y, d[u].z, d[u].w};
;           int s0 = 0, s1 = 0;
; #pragma unroll
;           for (int k = 0; k < 4; ++k) {
;             s0 = __builtin_amdgcn_sdot4((int)(w[k] & 0x0F0F0F0Fu), hq[2 * k], s0, false);
;             s1 = __builtin_amdgcn_sdot4((int)((w[k] >> 4) & 0x0F0F0F0Fu), hq[2 * k + 1], s1, false);
;           }
;           const int sI = wave_sum_i(s0 + s1);
;           if (lane == e + u) acti = sI;
;         }
.LBB0_851:
	v_readlane_b32 s0, v86, s4
	s_ashr_i32 s1, s0, 31
	s_lshl_b64 s[0:1], s[0:1], 10
	v_lshl_add_u64 v[50:51], v[66:67], 0, s[0:1]
	global_load_dwordx4 v[50:53], v[50:51], off
	s_add_i32 s5, s4, 1
	s_add_i32 s29, s4, 2
	s_add_i32 s30, s4, 3
	s_add_i32 s31, s4, 4
	s_add_i32 s33, s4, 5
	s_add_i32 s34, s4, 6
	s_add_i32 s35, s4, 7
	s_add_i32 s36, s4, 8
	s_add_i32 s37, s4, 9
	s_add_i32 s38, s4, 10
	s_add_i32 s39, s4, 11
	s_add_i32 s40, s4, 12
	s_add_i32 s41, s4, 13
	s_add_i32 s42, s4, 14
	s_add_i32 s43, s4, 15
	v_readlane_b32 s46, v86, s5
	v_readlane_b32 s48, v86, s29
	v_readlane_b32 s50, v86, s30
	v_readlane_b32 s52, v86, s31
	v_readlane_b32 s54, v86, s33
	v_readlane_b32 s56, v86, s34
	v_readlane_b32 s58, v86, s35
	v_readlane_b32 s60, v86, s36
	v_readlane_b32 s62, v86, s37
	v_readlane_b32 s64, v86, s38
	v_readlane_b32 s66, v86, s39
	v_readlane_b32 s68, v86, s40
	v_readlane_b32 s70, v86, s41
	v_readlane_b32 s72, v86, s42
	v_readlane_b32 s74, v86, s43
	s_ashr_i32 s47, s46, 31
	s_ashr_i32 s49, s48, 31
	s_ashr_i32 s51, s50, 31
	s_ashr_i32 s53, s52, 31
	s_ashr_i32 s55, s54, 31
	s_ashr_i32 s57, s56, 31
	s_ashr_i32 s59, s58, 31
	s_ashr_i32 s61, s60, 31
	s_ashr_i32 s63, s62, 31
	s_ashr_i32 s65, s64, 31
	s_ashr_i32 s67, s66, 31
	s_ashr_i32 s69, s68, 31
	s_ashr_i32 s71, s70, 31
	s_ashr_i32 s73, s72, 31
	s_ashr_i32 s75, s74, 31
	s_lshl_b64 s[0:1], s[46:47], 10
	s_lshl_b64 s[46:47], s[48:49], 10
	s_lshl_b64 s[48:49], s[50:51], 10
	s_lshl_b64 s[50:51], s[52:53], 10
	s_lshl_b64 s[52:53], s[54:55], 10
	s_lshl_b64 s[54:55], s[56:57], 10
	s_lshl_b64 s[56:57], s[58:59], 10
	s_lshl_b64 s[58:59], s[60:61], 10
	s_lshl_b64 s[60:61], s[62:63], 10
	s_lshl_b64 s[62:63], s[64:65], 10
	s_lshl_b64 s[64:65], s[66:67], 10
	s_lshl_b64 s[66:67], s[68:69], 10
	s_lshl_b64 s[68:69], s[70:71], 10
	s_lshl_b64 s[70:71], s[72:73], 10
	s_lshl_b64 s[72:73], s[74:75], 10
	v_lshl_add_u64 v[54:55], v[66:67], 0, s[0:1]
	v_lshl_add_u64 v[58:59], v[66:67], 0, s[46:47]
	v_lshl_add_u64 v[108:109], v[66:67], 0, s[50:51]
	v_lshl_add_u64 v[112:113], v[66:67], 0, s[52:53]
	v_lshl_add_u64 v[116:117], v[66:67], 0, s[54:55]
	v_lshl_add_u64 v[120:121], v[66:67], 0, s[56:57]
	v_lshl_add_u64 v[124:125], v[66:67], 0, s[58:59]
	v_lshl_add_u64 v[128:129], v[66:67], 0, s[60:61]
	v_lshl_add_u64 v[132:133], v[66:67], 0, s[62:63]
	v_lshl_add_u64 v[136:137], v[66:67], 0, s[64:65]
	v_lshl_add_u64 v[140:141], v[66:67], 0, s[66:67]
	v_lshl_add_u64 v[144:145], v[66:67], 0, s[68:69]
	v_lshl_add_u64 v[148:149], v[66:67], 0, s[70:71]
	v_lshl_add_u64 v[152:153], v[66:67], 0, s[72:73]
	v_lshl_add_u64 v[62:63], v[66:67], 0, s[48:49]
	global_load_dwordx4 v[54:57], v[54:55], off
	s_nop 0
	global_load_dwordx4 v[58:61], v[58:59], off
	s_nop 0
	global_load_dwordx4 v[104:107], v[62:63], off
	s_nop 0
	global_load_dwordx4 v[108:111], v[108:109], off
	s_nop 0
	global_load_dwordx4 v[112:115], v[112:113], off
	s_nop 0
	global_load_dwordx4 v[116:119], v[116:117], off
	s_nop 0
	global_load_dwordx4 v[120:123], v[120:121], off
	s_nop 0
	global_load_dwordx4 v[124:127], v[124:125], off
	s_nop 0
	global_load_dwordx4 v[128:131], v[128:129], off
	s_nop 0
	global_load_dwordx4 v[132:135], v[132:133], off
	s_nop 0
	global_load_dwordx4 v[136:139], v[136:137], off
	s_nop 0
	global_load_dwordx4 v[140:143], v[140:141], off
	s_nop 0
	global_load_dwordx4 v[144:147], v[144:145], off
	s_nop 0
	global_load_dwordx4 v[148:151], v[148:149], off
	s_nop 0
	global_load_dwordx4 v[152:155], v[152:153], off
	v_mov_b32_e32 v20, 0
	v_mov_b32_e32 v22, 0
	v_mov_b32_e32 v23, 0
	s_waitcnt vmcnt(15)
	v_and_b32_e32 v62, 0xf0f0f0f, v50
	v_lshrrev_b32_e32 v50, 4, v50
	v_and_b32_e32 v63, 0xf0f0f0f, v51
	v_lshrrev_b32_e32 v51, 4, v51
	v_dot4c_i32_i8_e32 v20, v62, v5
	v_and_b32_e32 v50, 0xf0f0f0f, v50
	v_mov_b32_e32 v24, 0
	v_and_b32_e32 v87, 0xf0f0f0f, v52
	v_lshrrev_b32_e32 v52, 4, v52
	v_and_b32_e32 v51, 0xf0f0f0f, v51
	v_dot4c_i32_i8_e32 v22, v50, v6
	v_mov_b32_e32 v25, 0
	v_mov_b32_e32 v26, 0
	v_mov_b32_e32 v29, 0
	v_mov_b32_e32 v30, 0
	v_mov_b32_e32 v37, 0
	v_mov_b32_e32 v38, 0
	v_and_b32_e32 v103, 0xf0f0f0f, v53
	v_lshrrev_b32_e32 v53, 4, v53
	v_and_b32_e32 v52, 0xf0f0f0f, v52
	v_dot4c_i32_i8_e32 v20, v63, v7
	v_dot4c_i32_i8_e32 v22, v51, v8
	v_mov_b32_e32 v27, 0
	v_mov_b32_e32 v28, 0
	v_mov_b32_e32 v31, 0
	v_mov_b32_e32 v32, 0
	v_mov_b32_e32 v39, 0
	v_mov_b32_e32 v40, 0
	v_and_b32_e32 v53, 0xf0f0f0f, v53
	v_dot4c_i32_i8_e32 v20, v87, v9
	v_dot4c_i32_i8_e32 v22, v52, v10
	v_dot4c_i32_i8_e32 v20, v103, v11
	v_dot4c_i32_i8_e32 v22, v53, v12
	v_mov_b32_e32 v41, 0
	v_mov_b32_e32 v42, 0
	v_mov_b32_e32 v33, 0
	v_add_u32_e32 v20, v22, v20
	v_mov_b32_e32 v34, 0
	v_mov_b32_e32 v35, 0
	v_mov_b32_e32 v36, 0
	v_mov_b32_e32 v43, 0
	v_mov_b32_e32 v44, 0
	v_mov_b32_e32 v45, 0
	v_mov_b32_e32 v46, 0
	v_mov_b32_e32 v47, 0
	v_mov_b32_e32 v48, 0
	v_mov_b32_e32 v49, 0
	v_mov_b32_e32 v77, 0
	v_mov_b32_e32 v79, 0
	v_mov_b32_e32 v83, 0
	s_waitcnt vmcnt(14)
	v_and_b32_e32 v62, 0xf0f0f0f, v54
	v_lshrrev_b32_e32 v54, 4, v54
	v_and_b32_e32 v156, 0xf0f0f0f, v55
	v_lshrrev_b32_e32 v55, 4, v55
	v_and_b32_e32 v157, 0xf0f0f0f, v56
	v_lshrrev_b32_e32 v56, 4, v56
	v_and_b32_e32 v158, 0xf0f0f0f, v57
	v_lshrrev_b32_e32 v57, 4, v57
	s_waitcnt vmcnt(13)
	v_and_b32_e32 v159, 0xf0f0f0f, v58
	v_lshrrev_b32_e32 v58, 4, v58
	s_waitcnt vmcnt(12)
	v_and_b32_e32 v164, 0xf0f0f0f, v105
	v_lshrrev_b32_e32 v105, 4, v105
	v_and_b32_e32 v165, 0xf0f0f0f, v106
	v_lshrrev_b32_e32 v106, 4, v106
	s_waitcnt vmcnt(11)
	v_and_b32_e32 v167, 0xf0f0f0f, v108
	v_lshrrev_b32_e32 v108, 4, v108
	v_and_b32_e32 v168, 0xf0f0f0f, v109
	v_lshrrev_b32_e32 v109, 4, v109
	s_waitcnt vmcnt(10)
; __device__ void peer_phase(const Params& p) {
;     ...
;         for (int u = 0; u < 16; ++u) {
;           const u32 w[4] = {d[u].x, d[u].y, d[u].z, d[u].w};
;           int s0 = 0, s1 = 0;
; #pragma unroll
;           for (int k = 0; k < 4; ++k) {
;             s0 = __builtin_amdgcn_sdot4((int)(w[k] & 0x0F0F0F0Fu), hq[2 * k], s0, false);
;             s1 = __builtin_amdgcn_sdot4((int)((w[k] >> 4) & 0x0F0F0F0Fu), hq[2 * k + 1], s1, false);
;           }
;           const int sI = wave_sum_i(s0 + s1);
	v_and_b32_e32 v171, 0xf0f0f0f, v112
	v_lshrrev_b32_e32 v112, 4, v112
	v_and_b32_e32 v174, 0xf0f0f0f, v115
	v_lshrrev_b32_e32 v115, 4, v115
	s_waitcnt vmcnt(9)
	v_and_b32_e32 v177, 0xf0f0f0f, v118
	v_lshrrev_b32_e32 v118, 4, v118
	s_waitcnt vmcnt(8)
	v_and_b32_e32 v180, 0xf0f0f0f, v121
	v_lshrrev_b32_e32 v121, 4, v121
	s_waitcnt vmcnt(7)
	v_and_b32_e32 v183, 0xf0f0f0f, v124
	v_lshrrev_b32_e32 v124, 4, v124
	v_and_b32_e32 v50, 0xf0f0f0f, v54
	v_and_b32_e32 v160, 0xf0f0f0f, v59
	v_lshrrev_b32_e32 v59, 4, v59
	v_and_b32_e32 v161, 0xf0f0f0f, v60
	v_lshrrev_b32_e32 v60, 4, v60
	v_and_b32_e32 v162, 0xf0f0f0f, v61
	v_lshrrev_b32_e32 v61, 4, v61
	v_and_b32_e32 v163, 0xf0f0f0f, v104
	v_lshrrev_b32_e32 v104, 4, v104
	v_and_b32_e32 v166, 0xf0f0f0f, v107
	v_lshrrev_b32_e32 v107, 4, v107
	v_and_b32_e32 v169, 0xf0f0f0f, v110
	v_lshrrev_b32_e32 v110, 4, v110
	v_and_b32_e32 v172, 0xf0f0f0f, v113
	v_lshrrev_b32_e32 v113, 4, v113
	v_and_b32_e32 v175, 0xf0f0f0f, v116
	v_lshrrev_b32_e32 v116, 4, v116
	v_and_b32_e32 v178, 0xf0f0f0f, v119
	v_lshrrev_b32_e32 v119, 4, v119
	v_and_b32_e32 v181, 0xf0f0f0f, v122
	v_lshrrev_b32_e32 v122, 4, v122
	v_and_b32_e32 v184, 0xf0f0f0f, v125
	v_lshrrev_b32_e32 v125, 4, v125
	s_waitcnt vmcnt(6)
	v_and_b32_e32 v187, 0xf0f0f0f, v128
	v_lshrrev_b32_e32 v128, 4, v128
	v_dot4c_i32_i8_e32 v23, v62, v5
	v_and_b32_e32 v54, 0xf0f0f0f, v55
	v_and_b32_e32 v55, 0xf0f0f0f, v56
	v_and_b32_e32 v56, 0xf0f0f0f, v57
	v_and_b32_e32 v57, 0xf0f0f0f, v58
	v_and_b32_e32 v62, 0xf0f0f0f, v105
	v_and_b32_e32 v63, 0xf0f0f0f, v106
	v_and_b32_e32 v105, 0xf0f0f0f, v108
	v_and_b32_e32 v106, 0xf0f0f0f, v109
	v_and_b32_e32 v109, 0xf0f0f0f, v112
	v_and_b32_e32 v112, 0xf0f0f0f, v115
	v_and_b32_e32 v115, 0xf0f0f0f, v118
	v_and_b32_e32 v118, 0xf0f0f0f, v121
	v_and_b32_e32 v121, 0xf0f0f0f, v124
	v_dot4c_i32_i8_e32 v24, v50, v6
	v_and_b32_e32 v170, 0xf0f0f0f, v111
	v_lshrrev_b32_e32 v111, 4, v111
	v_and_b32_e32 v173, 0xf0f0f0f, v114
	v_lshrrev_b32_e32 v114, 4, v114
	v_and_b32_e32 v176, 0xf0f0f0f, v117
	v_lshrrev_b32_e32 v117, 4, v117
	v_and_b32_e32 v179, 0xf0f0f0f, v120
	v_lshrrev_b32_e32 v120, 4, v120
	v_and_b32_e32 v182, 0xf0f0f0f, v123
	v_lshrrev_b32_e32 v123, 4, v123
	v_and_b32_e32 v185, 0xf0f0f0f, v126
	v_lshrrev_b32_e32 v126, 4, v126
	v_and_b32_e32 v188, 0xf0f0f0f, v129
	v_lshrrev_b32_e32 v129, 4, v129
	v_dot4c_i32_i8_e32 v25, v159, v5
	v_and_b32_e32 v58, 0xf0f0f0f, v59
	v_and_b32_e32 v59, 0xf0f0f0f, v60
	v_and_b32_e32 v60, 0xf0f0f0f, v61
	v_and_b32_e32 v61, 0xf0f0f0f, v104
	v_and_b32_e32 v104, 0xf0f0f0f, v107
	v_dot4c_i32_i8_e32 v29, v167, v5
	v_and_b32_e32 v107, 0xf0f0f0f, v110
	v_and_b32_e32 v110, 0xf0f0f0f, v113
	v_and_b32_e32 v113, 0xf0f0f0f, v116
	v_and_b32_e32 v116, 0xf0f0f0f, v119
	v_and_b32_e32 v119, 0xf0f0f0f, v122
	v_dot4c_i32_i8_e32 v37, v183, v5
	v_and_b32_e32 v122, 0xf0f0f0f, v125
	v_and_b32_e32 v125, 0xf0f0f0f, v128
	v_dot4c_i32_i8_e32 v23, v156, v7
	v_dot4c_i32_i8_e32 v26, v57, v6
	v_dot4c_i32_i8_e32 v30, v105, v6
	v_dot4c_i32_i8_e32 v38, v121, v6
	v_dot4c_i32_i8_e32 v24, v54, v8
	v_and_b32_e32 v186, 0xf0f0f0f, v127
	v_lshrrev_b32_e32 v127, 4, v127
	v_and_b32_e32 v189, 0xf0f0f0f, v130
	v_lshrrev_b32_e32 v130, 4, v130
	s_waitcnt vmcnt(5)
	v_and_b32_e32 v191, 0xf0f0f0f, v132
	v_lshrrev_b32_e32 v132, 4, v132
	v_dot4c_i32_i8_e32 v27, v163, v5
	v_and_b32_e32 v108, 0xf0f0f0f, v111
	v_dot4c_i32_i8_e32 v31, v171, v5
	v_and_b32_e32 v111, 0xf0f0f0f, v114
	v_and_b32_e32 v114, 0xf0f0f0f, v117
	v_and_b32_e32 v117, 0xf0f0f0f, v120
	v_and_b32_e32 v120, 0xf0f0f0f, v123
	v_and_b32_e32 v123, 0xf0f0f0f, v126
	v_dot4c_i32_i8_e32 v39, v187, v5
	v_and_b32_e32 v126, 0xf0f0f0f, v129
	v_dot4c_i32_i8_e32 v25, v160, v7
	v_dot4c_i32_i8_e32 v28, v61, v6
	v_dot4c_i32_i8_e32 v29, v168, v7
	v_dot4c_i32_i8_e32 v32, v109, v6
	v_dot4c_i32_i8_e32 v37, v184, v7
	v_dot4c_i32_i8_e32 v40, v125, v6
	v_dot4c_i32_i8_e32 v23, v157, v9
	v_dot4c_i32_i8_e32 v26, v58, v8
	v_dot4c_i32_i8_e32 v30, v106, v8
	v_dot4c_i32_i8_e32 v38, v122, v8
	v_dot4c_i32_i8_e32 v24, v55, v10
	v_and_b32_e32 v190, 0xf0f0f0f, v131
	v_lshrrev_b32_e32 v131, 4, v131
	v_and_b32_e32 v192, 0xf0f0f0f, v133
	v_lshrrev_b32_e32 v133, 4, v133
	v_and_b32_e32 v124, 0xf0f0f0f, v127
	v_and_b32_e32 v127, 0xf0f0f0f, v130
	v_and_b32_e32 v129, 0xf0f0f0f, v132
	v_dot4c_i32_i8_e32 v27, v164, v7
	v_dot4c_i32_i8_e32 v31, v172, v7
	v_dot4c_i32_i8_e32 v39, v188, v7
	v_dot4c_i32_i8_e32 v25, v161, v9
	v_dot4c_i32_i8_e32 v28, v62, v8
	v_dot4c_i32_i8_e32 v29, v169, v9
	v_dot4c_i32_i8_e32 v32, v110, v8
	v_dot4c_i32_i8_e32 v37, v185, v9
	v_dot4c_i32_i8_e32 v40, v126, v8
	v_dot4c_i32_i8_e32 v23, v158, v11
	v_dot4c_i32_i8_e32 v26, v59, v10
	v_dot4c_i32_i8_e32 v30, v107, v10
	v_dot4c_i32_i8_e32 v38, v123, v10
	v_dot4c_i32_i8_e32 v24, v56, v12
	v_and_b32_e32 v193, 0xf0f0f0f, v134
	v_lshrrev_b32_e32 v134, 4, v134
	s_waitcnt vmcnt(4)
	v_and_b32_e32 v195, 0xf0f0f0f, v136
	v_lshrrev_b32_e32 v136, 4, v136
	v_and_b32_e32 v128, 0xf0f0f0f, v131
	v_dot4c_i32_i8_e32 v41, v191, v5
	v_and_b32_e32 v130, 0xf0f0f0f, v133
	v_dot4c_i32_i8_e32 v42, v129, v6
	v_dot4c_i32_i8_e32 v27, v165, v9
	v_dot4c_i32_i8_e32 v31, v173, v9
	v_dot4c_i32_i8_e32 v39, v189, v9
	v_dot4c_i32_i8_e32 v25, v162, v11
	v_dot4c_i32_i8_e32 v28, v63, v10
	v_dot4c_i32_i8_e32 v29, v170, v11
	v_dot4c_i32_i8_e32 v32, v111, v10
	v_dot4c_i32_i8_e32 v37, v186, v11
	v_dot4c_i32_i8_e32 v40, v127, v10
	v_dot4c_i32_i8_e32 v26, v60, v12
	v_dot4c_i32_i8_e32 v30, v108, v12
	v_dot4c_i32_i8_e32 v38, v124, v12
	v_add_u32_e32 v23, v24, v23
	v_and_b32_e32 v194, 0xf0f0f0f, v135
	v_lshrrev_b32_e32 v135, 4, v135
	v_and_b32_e32 v196, 0xf0f0f0f, v137
	v_lshrrev_b32_e32 v137, 4, v137
	v_dot4c_i32_i8_e32 v33, v175, v5
	v_and_b32_e32 v131, 0xf0f0f0f, v134
	v_and_b32_e32 v133, 0xf0f0f0f, v136
	v_dot4c_i32_i8_e32 v34, v113, v6
	v_dot4c_i32_i8_e32 v41, v192, v7
	v_dot4c_i32_i8_e32 v42, v130, v8
	v_dot4c_i32_i8_e32 v27, v166, v11
	v_dot4c_i32_i8_e32 v31, v174, v11
	v_dot4c_i32_i8_e32 v39, v190, v11
	v_dot4c_i32_i8_e32 v28, v104, v12
	v_dot4c_i32_i8_e32 v32, v112, v12
	v_dot4c_i32_i8_e32 v40, v128, v12
	v_add_u32_e32 v24, v26, v25
	v_add_u32_e32 v26, v30, v29
	v_add_u32_e32 v30, v38, v37
	v_and_b32_e32 v197, 0xf0f0f0f, v138
	v_lshrrev_b32_e32 v138, 4, v138
	s_waitcnt vmcnt(3)
; __device__ void peer_phase(const Params& p) {
;     ...
;         for (int u = 0; u < 16; ++u) {
;           const u32 w[4] = {d[u].x, d[u].y, d[u].z, d[u].w};
;           int s0 = 0, s1 = 0;
; #pragma unroll
;           for (int k = 0; k < 4; ++k) {
;             s0 = __builtin_amdgcn_sdot4((int)(w[k] & 0x0F0F0F0Fu), hq[2 * k], s0, false);
;             s1 = __builtin_amdgcn_sdot4((int)((w[k] >> 4) & 0x0F0F0F0Fu), hq[2 * k + 1], s1, false);
;           }
;           const int sI = wave_sum_i(s0 + s1);
	v_and_b32_e32 v199, 0xf0f0f0f, v140
	v_lshrrev_b32_e32 v140, 4, v140
	v_dot4c_i32_i8_e32 v35, v179, v5
	v_and_b32_e32 v132, 0xf0f0f0f, v135
	v_dot4c_i32_i8_e32 v43, v195, v5
	v_and_b32_e32 v134, 0xf0f0f0f, v137
	v_dot4c_i32_i8_e32 v33, v176, v7
	v_dot4c_i32_i8_e32 v36, v117, v6
	v_dot4c_i32_i8_e32 v44, v133, v6
	v_dot4c_i32_i8_e32 v34, v114, v8
	v_dot4c_i32_i8_e32 v41, v193, v9
	v_dot4c_i32_i8_e32 v42, v131, v10
	v_add_u32_e32 v25, v28, v27
	v_add_u32_e32 v27, v32, v31
	v_add_u32_e32 v31, v40, v39
	v_and_b32_e32 v198, 0xf0f0f0f, v139
	v_lshrrev_b32_e32 v139, 4, v139
	v_and_b32_e32 v200, 0xf0f0f0f, v141
	v_lshrrev_b32_e32 v141, 4, v141
	v_and_b32_e32 v135, 0xf0f0f0f, v138
	v_and_b32_e32 v137, 0xf0f0f0f, v140
	v_dot4c_i32_i8_e32 v35, v180, v7
	v_dot4c_i32_i8_e32 v43, v196, v7
	v_dot4c_i32_i8_e32 v33, v177, v9
	v_dot4c_i32_i8_e32 v36, v118, v8
	v_dot4c_i32_i8_e32 v44, v134, v8
	v_dot4c_i32_i8_e32 v34, v115, v10
	v_dot4c_i32_i8_e32 v41, v194, v11
	v_dot4c_i32_i8_e32 v42, v132, v12
	v_and_b32_e32 v201, 0xf0f0f0f, v142
	v_lshrrev_b32_e32 v142, 4, v142
	s_waitcnt vmcnt(2)
	v_and_b32_e32 v203, 0xf0f0f0f, v144
	v_lshrrev_b32_e32 v144, 4, v144
	v_and_b32_e32 v136, 0xf0f0f0f, v139
	v_dot4c_i32_i8_e32 v45, v199, v5
	v_and_b32_e32 v138, 0xf0f0f0f, v141
	v_dot4c_i32_i8_e32 v46, v137, v6
	v_dot4c_i32_i8_e32 v35, v181, v9
	v_dot4c_i32_i8_e32 v43, v197, v9
	v_dot4c_i32_i8_e32 v33, v178, v11
	v_dot4c_i32_i8_e32 v36, v119, v10
	v_dot4c_i32_i8_e32 v44, v135, v10
	v_dot4c_i32_i8_e32 v34, v116, v12
	v_add_u32_e32 v32, v42, v41
	v_and_b32_e32 v202, 0xf0f0f0f, v143
	v_lshrrev_b32_e32 v143, 4, v143
	v_and_b32_e32 v204, 0xf0f0f0f, v145
	v_lshrrev_b32_e32 v145, 4, v145
	v_and_b32_e32 v139, 0xf0f0f0f, v142
	v_and_b32_e32 v141, 0xf0f0f0f, v144
	v_dot4c_i32_i8_e32 v45, v200, v7
	v_dot4c_i32_i8_e32 v46, v138, v8
	v_dot4c_i32_i8_e32 v35, v182, v11
	v_dot4c_i32_i8_e32 v43, v198, v11
	v_dot4c_i32_i8_e32 v36, v120, v12
	v_dot4c_i32_i8_e32 v44, v136, v12
	v_add_u32_e32 v28, v34, v33
	v_and_b32_e32 v205, 0xf0f0f0f, v146
	v_lshrrev_b32_e32 v146, 4, v146
	s_waitcnt vmcnt(1)
	v_and_b32_e32 v207, 0xf0f0f0f, v148
	v_lshrrev_b32_e32 v148, 4, v148
	v_and_b32_e32 v140, 0xf0f0f0f, v143
	v_dot4c_i32_i8_e32 v47, v203, v5
	v_and_b32_e32 v142, 0xf0f0f0f, v145
	v_dot4c_i32_i8_e32 v48, v141, v6
	v_dot4c_i32_i8_e32 v45, v201, v9
	v_dot4c_i32_i8_e32 v46, v139, v10
	v_add_u32_e32 v29, v36, v35
	v_add_u32_e32 v33, v44, v43
	v_and_b32_e32 v206, 0xf0f0f0f, v147
	v_lshrrev_b32_e32 v147, 4, v147
	v_and_b32_e32 v208, 0xf0f0f0f, v149
	v_lshrrev_b32_e32 v149, 4, v149
	v_and_b32_e32 v143, 0xf0f0f0f, v146
	v_and_b32_e32 v145, 0xf0f0f0f, v148
	v_dot4c_i32_i8_e32 v47, v204, v7
	v_dot4c_i32_i8_e32 v48, v142, v8
	v_dot4c_i32_i8_e32 v45, v202, v11
	v_dot4c_i32_i8_e32 v46, v140, v12
	v_and_b32_e32 v209, 0xf0f0f0f, v150
	v_lshrrev_b32_e32 v150, 4, v150
	s_waitcnt vmcnt(0)
; __device__ void peer_phase(const Params& p) {
;     ...
;         for (int u = 0; u < 16; ++u) {
;           const u32 w[4] = {d[u].x, d[u].y, d[u].z, d[u].w};
;           int s0 = 0, s1 = 0;
; #pragma unroll
;           for (int k = 0; k < 4; ++k) {
;             s0 = __builtin_amdgcn_sdot4((int)(w[k] & 0x0F0F0F0Fu), hq[2 * k], s0, false);
;             s1 = __builtin_amdgcn_sdot4((int)((w[k] >> 4) & 0x0F0F0F0Fu), hq[2 * k + 1], s1, false);
;           }
;           const int sI = wave_sum_i(s0 + s1);
;           if (lane == e + u) acti = sI;
;         }
;       }
;       const float act = ((float)acti - 7.5f * (float)hsum) * sh * (hf == 0 ? ds0 : ds1);
;       gg[hf] *= 0.5f * act * (1.f + erff(act * 0.70710678118654752f)) * (hf == 0 ? us0 : us1);
	v_and_b32_e32 v211, 0xf0f0f0f, v152
	v_lshrrev_b32_e32 v152, 4, v152
	v_and_b32_e32 v144, 0xf0f0f0f, v147
	v_dot4c_i32_i8_e32 v49, v207, v5
	v_and_b32_e32 v146, 0xf0f0f0f, v149
	v_dot4c_i32_i8_e32 v77, v145, v6
	v_dot4c_i32_i8_e32 v47, v205, v9
	v_dot4c_i32_i8_e32 v48, v143, v10
	v_add_u32_e32 v34, v46, v45
	v_and_b32_e32 v210, 0xf0f0f0f, v151
	v_lshrrev_b32_e32 v151, 4, v151
	v_and_b32_e32 v212, 0xf0f0f0f, v153
	v_lshrrev_b32_e32 v153, 4, v153
	v_and_b32_e32 v147, 0xf0f0f0f, v150
	v_and_b32_e32 v149, 0xf0f0f0f, v152
	v_dot4c_i32_i8_e32 v49, v208, v7
	v_dot4c_i32_i8_e32 v77, v146, v8
	v_dot4c_i32_i8_e32 v47, v206, v11
	v_dot4c_i32_i8_e32 v48, v144, v12
	v_and_b32_e32 v213, 0xf0f0f0f, v154
	v_lshrrev_b32_e32 v154, 4, v154
	v_and_b32_e32 v148, 0xf0f0f0f, v151
	v_dot4c_i32_i8_e32 v79, v211, v5
	v_and_b32_e32 v150, 0xf0f0f0f, v153
	v_dot4c_i32_i8_e32 v83, v149, v6
	v_dot4c_i32_i8_e32 v49, v209, v9
	v_dot4c_i32_i8_e32 v77, v147, v10
	v_add_u32_e32 v35, v48, v47
	v_and_b32_e32 v214, 0xf0f0f0f, v155
	v_lshrrev_b32_e32 v155, 4, v155
	v_and_b32_e32 v151, 0xf0f0f0f, v154
	v_dot4c_i32_i8_e32 v79, v212, v7
	v_dot4c_i32_i8_e32 v83, v150, v8
	v_dot4c_i32_i8_e32 v49, v210, v11
	v_dot4c_i32_i8_e32 v77, v148, v12
	v_and_b32_e32 v152, 0xf0f0f0f, v155
	v_dot4c_i32_i8_e32 v79, v213, v9
	v_dot4c_i32_i8_e32 v83, v151, v10
	v_add_u32_e32 v36, v77, v49
	v_dot4c_i32_i8_e32 v79, v214, v11
	v_dot4c_i32_i8_e32 v83, v152, v12
	s_nop 2
	v_add_u32_e32 v37, v83, v79
	s_mov_b32 s0, s4
	s_add_i32 s44, s4, 16
	s_cmp_gt_u32 s0, 47
	s_mov_b32 s4, s44
	s_nop 1
	v_add_u32_dpp v38, v20, v20 row_mirror row_mask:0xf bank_mask:0x3
	v_add_u32_dpp v38, v30, v30 row_mirror row_mask:0xf bank_mask:0xc
	v_add_u32_dpp v39, v23, v23 row_mirror row_mask:0xf bank_mask:0x3
	v_add_u32_dpp v39, v31, v31 row_mirror row_mask:0xf bank_mask:0xc
	v_add_u32_dpp v40, v24, v24 row_mirror row_mask:0xf bank_mask:0x3
	v_add_u32_dpp v40, v32, v32 row_mirror row_mask:0xf bank_mask:0xc
	v_add_u32_dpp v41, v25, v25 row_mirror row_mask:0xf bank_mask:0x3
	v_add_u32_dpp v41, v33, v33 row_mirror row_mask:0xf bank_mask:0xc
	v_add_u32_dpp v42, v26, v26 row_mirror row_mask:0xf bank_mask:0x3
	v_add_u32_dpp v42, v34, v34 row_mirror row_mask:0xf bank_mask:0xc
	v_add_u32_dpp v43, v27, v27 row_mirror row_mask:0xf bank_mask:0x3
	v_add_u32_dpp v43, v35, v35 row_mirror row_mask:0xf bank_mask:0xc
	v_add_u32_dpp v44, v28, v28 row_mirror row_mask:0xf bank_mask:0x3
	v_add_u32_dpp v44, v36, v36 row_mirror row_mask:0xf bank_mask:0xc
	v_add_u32_dpp v45, v29, v29 row_mirror row_mask:0xf bank_mask:0x3
	v_add_u32_dpp v45, v37, v37 row_mirror row_mask:0xf bank_mask:0xc
	v_add_u32_dpp v46, v38, v38 row_half_mirror row_mask:0xf bank_mask:0x5
	v_add_u32_dpp v46, v42, v42 row_half_mirror row_mask:0xf bank_mask:0xa
	v_add_u32_dpp v47, v39, v39 row_half_mirror row_mask:0xf bank_mask:0x5
	v_add_u32_dpp v47, v43, v43 row_half_mirror row_mask:0xf bank_mask:0xa
	v_add_u32_dpp v48, v40, v40 row_half_mirror row_mask:0xf bank_mask:0x5
	v_add_u32_dpp v48, v44, v44 row_half_mirror row_mask:0xf bank_mask:0xa
	v_add_u32_dpp v49, v41, v41 row_half_mirror row_mask:0xf bank_mask:0x5
	v_add_u32_dpp v49, v45, v45 row_half_mirror row_mask:0xf bank_mask:0xa
	v_add_u32_dpp v46, v46, v46 quad_perm:[1,0,3,2] row_mask:0xf bank_mask:0xf
	v_add_u32_dpp v47, v47, v47 quad_perm:[1,0,3,2] row_mask:0xf bank_mask:0xf
	v_add_u32_dpp v48, v48, v48 quad_perm:[1,0,3,2] row_mask:0xf bank_mask:0xf
	v_add_u32_dpp v49, v49, v49 quad_perm:[1,0,3,2] row_mask:0xf bank_mask:0xf
	v_add_u32_dpp v46, v46, v46 quad_perm:[2,3,0,1] row_mask:0xf bank_mask:0xf
	v_add_u32_dpp v47, v47, v47 quad_perm:[2,3,0,1] row_mask:0xf bank_mask:0xf
	v_add_u32_dpp v48, v48, v48 quad_perm:[2,3,0,1] row_mask:0xf bank_mask:0xf
	v_add_u32_dpp v49, v49, v49 quad_perm:[2,3,0,1] row_mask:0xf bank_mask:0xf
	s_mov_b32 vcc_lo, 0x22222222
	s_mov_b32 vcc_hi, 0x22222222
	s_nop 1
	v_cndmask_b32_e32 v46, v46, v47, vcc
	s_mov_b32 vcc_lo, 0x44444444
	s_mov_b32 vcc_hi, 0x44444444
	s_nop 1
	v_cndmask_b32_e32 v46, v46, v48, vcc
	s_mov_b32 vcc_lo, 0x88888888
	s_mov_b32 vcc_hi, 0x88888888
	s_nop 1
	v_cndmask_b32_e32 v46, v46, v49, vcc
	ds_bpermute_b32 v50, v90, v46
	v_and_b32_e32 v47, 48, v88
	v_cmp_eq_u32_e32 vcc, s0, v47
	s_waitcnt lgkmcnt(0)
	v_add_u32_e32 v46, v50, v46
	ds_bpermute_b32 v50, v89, v46
	s_waitcnt lgkmcnt(0)
	v_add_u32_e32 v46, v50, v46
	s_nop 1
	v_cndmask_b32_e32 v21, v21, v46, vcc
	s_cbranch_scc0 .LBB0_851
	v_add_f32_e32 v19, v4, v19
	ds_bpermute_b32 v20, v92, v19
	v_add_f32_e32 v18, v2, v18
	ds_bpermute_b32 v22, v92, v18
	v_add_u32_e32 v14, v14, v15
	v_mul_f32_e32 v13, 0x3c010204, v13
	s_waitcnt lgkmcnt(1)
	v_add_f32_e32 v15, v19, v20
	ds_bpermute_b32 v19, v93, v15
	s_waitcnt lgkmcnt(1)
	v_add_f32_e32 v18, v18, v22
	ds_bpermute_b32 v23, v93, v18
	v_mul_f32_e32 v20, v13, v17
	v_cvt_f32_i32_e32 v22, v14
	s_waitcnt lgkmcnt(1)
	v_add_f32_e32 v17, v15, v19
	v_cvt_f32_i32_e32 v15, v21
	s_waitcnt lgkmcnt(0)
	v_add_f32_e32 v13, v18, v23
	ds_bpermute_b32 v18, v94, v17
	ds_bpermute_b32 v14, v94, v13
	v_fmac_f32_e32 v15, 0xc0f00000, v22
	v_mul_f32_e32 v15, v20, v15
	v_mul_f32_e32 v15, v16, v15
	v_mul_f32_e32 v16, 0x3f3504f3, v15
	v_cmp_nlt_f32_e64 s[0:1], |v16|, 1.0
	s_and_saveexec_b64 s[4:5], s[0:1]
	s_xor_b64 s[0:1], exec, s[4:5]
	s_cbranch_execz .LBB0_854
	v_fma_f32 v19, |v16|, s12, v100
	v_fma_f32 v19, |v16|, v19, s13
	v_fma_f32 v19, |v16|, v19, s14
	v_fma_f32 v19, |v16|, v19, s15
	v_fma_f32 v19, |v16|, v19, s16
	v_fma_f32 v19, |v16|, v19, s17
	v_fma_f32 v19, |v16|, v19, |v16|
	v_mul_f32_e32 v21, 0xbfb8aa3b, v19
	v_fma_f32 v23, v19, s18, -v21
	v_rndne_f32_e32 v24, v21
	v_fmac_f32_e32 v23, 0xb2a5705f, v19
	v_sub_f32_e32 v21, v21, v24
	v_add_f32_e32 v21, v21, v23
	v_cvt_i32_f32_e32 v23, v24
	v_exp_f32_e32 v21, v21
	v_cmp_nlt_f32_e32 vcc, s19, v19
	v_ldexp_f32 v21, v21, v23
	s_nop 0
	v_cndmask_b32_e32 v21, 0, v21, vcc
	v_cmp_ngt_f32_e32 vcc, s20, v19
	s_nop 1
	v_cndmask_b32_e32 v19, v101, v21, vcc
	v_sub_f32_e32 v19, 1.0, v19

; __device__ void peer_phase(const Params& p) {
;     ...
;     for (int hf = 0; hf < 2; ++hf) {
;       int acti = 0;
;       for (int e = 0; e < 64; e += 16) {
;         uint4 d[16];
; #pragma unroll
;         for (int u = 0; u < 16; ++u) {
;           const int id = __builtin_amdgcn_readlane(eid[hf], e + u);
;           d[u] = ((const uint4*)(down4 + (size_t)id * 1024))[lane];
;         }
; #pragma unroll
;         for (int u = 0; u < 16; ++u) {
;           const u32 w[4] = {d[u].x, d[u].y, d[u].z, d[u].w};
;           int s0 = 0, s1 = 0;
; #pragma unroll
;           for (int k = 0; k < 4; ++k) {
;             s0 = __builtin_amdgcn_sdot4((int)(w[k] & 0x0F0F0F0Fu), hq[2 * k], s0, false);
;             s1 = __builtin_amdgcn_sdot4((int)((w[k] >> 4) & 0x0F0F0F0Fu), hq[2 * k + 1], s1, false);
;           }
;           const int sI = wave_sum_i(s0 + s1);
;           if (lane == e + u) acti = sI;
;         }
.LBB0_857:
	v_readlane_b32 s0, v82, s4
	s_ashr_i32 s1, s0, 31
	s_lshl_b64 s[0:1], s[0:1], 10
	v_lshl_add_u64 v[52:53], v[66:67], 0, s[0:1]
	global_load_dwordx4 v[52:55], v[52:53], off
	s_add_i32 s5, s4, 1
	s_add_i32 s29, s4, 2
	s_add_i32 s30, s4, 3
	s_add_i32 s31, s4, 4
	s_add_i32 s33, s4, 5
	s_add_i32 s34, s4, 6
	s_add_i32 s35, s4, 7
	s_add_i32 s36, s4, 8
	s_add_i32 s37, s4, 9
	s_add_i32 s38, s4, 10
	s_add_i32 s39, s4, 11
	s_add_i32 s40, s4, 12
	s_add_i32 s41, s4, 13
	s_add_i32 s42, s4, 14
	s_add_i32 s43, s4, 15
	v_readlane_b32 s46, v82, s5
	v_readlane_b32 s48, v82, s29
	v_readlane_b32 s50, v82, s30
	v_readlane_b32 s52, v82, s31
	v_readlane_b32 s54, v82, s33
	v_readlane_b32 s56, v82, s34
	v_readlane_b32 s58, v82, s35
	v_readlane_b32 s60, v82, s36
	v_readlane_b32 s62, v82, s37
	v_readlane_b32 s64, v82, s38
	v_readlane_b32 s66, v82, s39
	v_readlane_b32 s68, v82, s40
	v_readlane_b32 s70, v82, s41
	v_readlane_b32 s72, v82, s42
	v_readlane_b32 s74, v82, s43
	s_ashr_i32 s47, s46, 31
	s_ashr_i32 s49, s48, 31
	s_ashr_i32 s51, s50, 31
	s_ashr_i32 s53, s52, 31
	s_ashr_i32 s55, s54, 31
	s_ashr_i32 s57, s56, 31
	s_ashr_i32 s59, s58, 31
	s_ashr_i32 s61, s60, 31
	s_ashr_i32 s63, s62, 31
	s_ashr_i32 s65, s64, 31
	s_ashr_i32 s67, s66, 31
	s_ashr_i32 s69, s68, 31
	s_ashr_i32 s71, s70, 31
	s_ashr_i32 s73, s72, 31
	s_ashr_i32 s75, s74, 31
	s_lshl_b64 s[0:1], s[46:47], 10
	s_lshl_b64 s[46:47], s[48:49], 10
	s_lshl_b64 s[48:49], s[50:51], 10
	s_lshl_b64 s[50:51], s[52:53], 10
	s_lshl_b64 s[52:53], s[54:55], 10
	s_lshl_b64 s[54:55], s[56:57], 10
	s_lshl_b64 s[56:57], s[58:59], 10
	s_lshl_b64 s[58:59], s[60:61], 10
	s_lshl_b64 s[60:61], s[62:63], 10
	s_lshl_b64 s[62:63], s[64:65], 10
	s_lshl_b64 s[64:65], s[66:67], 10
	s_lshl_b64 s[66:67], s[68:69], 10
	s_lshl_b64 s[68:69], s[70:71], 10
	s_lshl_b64 s[70:71], s[72:73], 10
	s_lshl_b64 s[72:73], s[74:75], 10
	v_lshl_add_u64 v[56:57], v[66:67], 0, s[0:1]
	v_lshl_add_u64 v[60:61], v[66:67], 0, s[46:47]
	v_lshl_add_u64 v[104:105], v[66:67], 0, s[48:49]
	v_lshl_add_u64 v[108:109], v[66:67], 0, s[50:51]
	v_lshl_add_u64 v[112:113], v[66:67], 0, s[52:53]
	v_lshl_add_u64 v[116:117], v[66:67], 0, s[54:55]
	v_lshl_add_u64 v[120:121], v[66:67], 0, s[56:57]
	v_lshl_add_u64 v[124:125], v[66:67], 0, s[58:59]
	v_lshl_add_u64 v[128:129], v[66:67], 0, s[60:61]
	v_lshl_add_u64 v[132:133], v[66:67], 0, s[62:63]
	v_lshl_add_u64 v[136:137], v[66:67], 0, s[64:65]
	v_lshl_add_u64 v[140:141], v[66:67], 0, s[66:67]
	v_lshl_add_u64 v[144:145], v[66:67], 0, s[68:69]
	v_lshl_add_u64 v[148:149], v[66:67], 0, s[70:71]
	v_lshl_add_u64 v[152:153], v[66:67], 0, s[72:73]
	global_load_dwordx4 v[56:59], v[56:57], off
	s_nop 0
	global_load_dwordx4 v[60:63], v[60:61], off
	s_nop 0
	global_load_dwordx4 v[104:107], v[104:105], off
	s_nop 0
	global_load_dwordx4 v[108:111], v[108:109], off
	s_nop 0
	global_load_dwordx4 v[112:115], v[112:113], off
	s_nop 0
	global_load_dwordx4 v[116:119], v[116:117], off
	s_nop 0
	global_load_dwordx4 v[120:123], v[120:121], off
	s_nop 0
	global_load_dwordx4 v[124:127], v[124:125], off
	s_nop 0
	global_load_dwordx4 v[128:131], v[128:129], off
	s_nop 0
	global_load_dwordx4 v[132:135], v[132:133], off
	s_nop 0
	global_load_dwordx4 v[136:139], v[136:137], off
	s_nop 0
	global_load_dwordx4 v[140:143], v[140:141], off
	s_nop 0
	global_load_dwordx4 v[144:147], v[144:145], off
	s_nop 0
	global_load_dwordx4 v[148:151], v[148:149], off
	s_nop 0
	global_load_dwordx4 v[152:155], v[152:153], off
	v_mov_b32_e32 v23, 0
	v_mov_b32_e32 v24, 0
	v_mov_b32_e32 v25, 0
	s_waitcnt vmcnt(15)
	v_and_b32_e32 v87, 0xf0f0f0f, v52
	v_lshrrev_b32_e32 v52, 4, v52
	v_and_b32_e32 v103, 0xf0f0f0f, v53
	v_lshrrev_b32_e32 v53, 4, v53
	v_dot4c_i32_i8_e32 v23, v87, v5
	v_and_b32_e32 v52, 0xf0f0f0f, v52
	v_mov_b32_e32 v26, 0
	v_and_b32_e32 v156, 0xf0f0f0f, v54
	v_lshrrev_b32_e32 v54, 4, v54
	v_and_b32_e32 v53, 0xf0f0f0f, v53
	v_dot4c_i32_i8_e32 v24, v52, v6
	v_mov_b32_e32 v27, 0
	v_mov_b32_e32 v28, 0
	v_mov_b32_e32 v31, 0
	v_mov_b32_e32 v32, 0
	v_mov_b32_e32 v39, 0
	v_mov_b32_e32 v40, 0
	v_and_b32_e32 v157, 0xf0f0f0f, v55
	v_lshrrev_b32_e32 v55, 4, v55
	v_and_b32_e32 v54, 0xf0f0f0f, v54
	v_dot4c_i32_i8_e32 v23, v103, v7
	v_dot4c_i32_i8_e32 v24, v53, v8
	v_mov_b32_e32 v29, 0
	v_mov_b32_e32 v30, 0
	v_mov_b32_e32 v33, 0
	v_mov_b32_e32 v34, 0
	v_mov_b32_e32 v41, 0
	v_mov_b32_e32 v42, 0
	v_and_b32_e32 v55, 0xf0f0f0f, v55
	v_dot4c_i32_i8_e32 v23, v156, v9
	v_dot4c_i32_i8_e32 v24, v54, v10
	v_dot4c_i32_i8_e32 v23, v157, v11
	v_dot4c_i32_i8_e32 v24, v55, v12
	v_mov_b32_e32 v43, 0
	v_mov_b32_e32 v44, 0
	v_mov_b32_e32 v35, 0
	v_add_u32_e32 v23, v24, v23
	v_mov_b32_e32 v36, 0
	v_mov_b32_e32 v37, 0
	v_mov_b32_e32 v38, 0
	v_mov_b32_e32 v45, 0
	v_mov_b32_e32 v46, 0
	v_mov_b32_e32 v47, 0
	v_mov_b32_e32 v48, 0
	v_mov_b32_e32 v49, 0
	v_mov_b32_e32 v50, 0
	v_mov_b32_e32 v51, 0
	v_mov_b32_e32 v77, 0
	v_mov_b32_e32 v79, 0
	v_mov_b32_e32 v83, 0
	s_cmp_lt_u32 s4, 48
	s_waitcnt vmcnt(14)
	v_and_b32_e32 v87, 0xf0f0f0f, v56
	v_lshrrev_b32_e32 v56, 4, v56
	v_and_b32_e32 v158, 0xf0f0f0f, v57
	v_lshrrev_b32_e32 v57, 4, v57
	v_and_b32_e32 v159, 0xf0f0f0f, v58
	v_lshrrev_b32_e32 v58, 4, v58
	v_and_b32_e32 v160, 0xf0f0f0f, v59
	v_lshrrev_b32_e32 v59, 4, v59
	s_waitcnt vmcnt(13)
	v_and_b32_e32 v161, 0xf0f0f0f, v60
	v_lshrrev_b32_e32 v60, 4, v60
	s_waitcnt vmcnt(12)
	v_and_b32_e32 v166, 0xf0f0f0f, v105
	v_lshrrev_b32_e32 v105, 4, v105
	v_and_b32_e32 v167, 0xf0f0f0f, v106
	v_lshrrev_b32_e32 v106, 4, v106
	s_waitcnt vmcnt(11)
	v_and_b32_e32 v169, 0xf0f0f0f, v108
	v_lshrrev_b32_e32 v108, 4, v108
	v_and_b32_e32 v170, 0xf0f0f0f, v109
	v_lshrrev_b32_e32 v109, 4, v109
	s_waitcnt vmcnt(10)
; __device__ void peer_phase(const Params& p) {
;     ...
;         for (int u = 0; u < 16; ++u) {
;           const u32 w[4] = {d[u].x, d[u].y, d[u].z, d[u].w};
;           int s0 = 0, s1 = 0;
; #pragma unroll
;           for (int k = 0; k < 4; ++k) {
;             s0 = __builtin_amdgcn_sdot4((int)(w[k] & 0x0F0F0F0Fu), hq[2 * k], s0, false);
;             s1 = __builtin_amdgcn_sdot4((int)((w[k] >> 4) & 0x0F0F0F0Fu), hq[2 * k + 1], s1, false);
;           }
;           const int sI = wave_sum_i(s0 + s1);
	v_and_b32_e32 v173, 0xf0f0f0f, v112
	v_lshrrev_b32_e32 v112, 4, v112
	v_and_b32_e32 v176, 0xf0f0f0f, v115
	v_lshrrev_b32_e32 v115, 4, v115
	s_waitcnt vmcnt(9)
	v_and_b32_e32 v179, 0xf0f0f0f, v118
	v_lshrrev_b32_e32 v118, 4, v118
	s_waitcnt vmcnt(8)
	v_and_b32_e32 v182, 0xf0f0f0f, v121
	v_lshrrev_b32_e32 v121, 4, v121
	s_waitcnt vmcnt(7)
	v_and_b32_e32 v185, 0xf0f0f0f, v124
	v_lshrrev_b32_e32 v124, 4, v124
	v_and_b32_e32 v52, 0xf0f0f0f, v56
	v_and_b32_e32 v162, 0xf0f0f0f, v61
	v_lshrrev_b32_e32 v61, 4, v61
	v_and_b32_e32 v163, 0xf0f0f0f, v62
	v_lshrrev_b32_e32 v62, 4, v62
	v_and_b32_e32 v164, 0xf0f0f0f, v63
	v_lshrrev_b32_e32 v63, 4, v63
	v_and_b32_e32 v165, 0xf0f0f0f, v104
	v_lshrrev_b32_e32 v104, 4, v104
	v_and_b32_e32 v168, 0xf0f0f0f, v107
	v_lshrrev_b32_e32 v107, 4, v107
	v_and_b32_e32 v171, 0xf0f0f0f, v110
	v_lshrrev_b32_e32 v110, 4, v110
	v_and_b32_e32 v174, 0xf0f0f0f, v113
	v_lshrrev_b32_e32 v113, 4, v113
	v_and_b32_e32 v177, 0xf0f0f0f, v116
	v_lshrrev_b32_e32 v116, 4, v116
	v_and_b32_e32 v180, 0xf0f0f0f, v119
	v_lshrrev_b32_e32 v119, 4, v119
	v_and_b32_e32 v183, 0xf0f0f0f, v122
	v_lshrrev_b32_e32 v122, 4, v122
	v_and_b32_e32 v186, 0xf0f0f0f, v125
	v_lshrrev_b32_e32 v125, 4, v125
	s_waitcnt vmcnt(6)
	v_and_b32_e32 v189, 0xf0f0f0f, v128
	v_lshrrev_b32_e32 v128, 4, v128
	v_dot4c_i32_i8_e32 v25, v87, v5
	v_and_b32_e32 v56, 0xf0f0f0f, v57
	v_and_b32_e32 v57, 0xf0f0f0f, v58
	v_and_b32_e32 v58, 0xf0f0f0f, v59
	v_and_b32_e32 v59, 0xf0f0f0f, v60
	v_and_b32_e32 v87, 0xf0f0f0f, v105
	v_and_b32_e32 v103, 0xf0f0f0f, v106
	v_and_b32_e32 v105, 0xf0f0f0f, v108
	v_and_b32_e32 v106, 0xf0f0f0f, v109
	v_and_b32_e32 v109, 0xf0f0f0f, v112
	v_and_b32_e32 v112, 0xf0f0f0f, v115
	v_and_b32_e32 v115, 0xf0f0f0f, v118
	v_and_b32_e32 v118, 0xf0f0f0f, v121
	v_and_b32_e32 v121, 0xf0f0f0f, v124
	v_dot4c_i32_i8_e32 v26, v52, v6
	v_and_b32_e32 v172, 0xf0f0f0f, v111
	v_lshrrev_b32_e32 v111, 4, v111
	v_and_b32_e32 v175, 0xf0f0f0f, v114
	v_lshrrev_b32_e32 v114, 4, v114
	v_and_b32_e32 v178, 0xf0f0f0f, v117
	v_lshrrev_b32_e32 v117, 4, v117
	v_and_b32_e32 v181, 0xf0f0f0f, v120
	v_lshrrev_b32_e32 v120, 4, v120
	v_and_b32_e32 v184, 0xf0f0f0f, v123
	v_lshrrev_b32_e32 v123, 4, v123
	v_and_b32_e32 v187, 0xf0f0f0f, v126
	v_lshrrev_b32_e32 v126, 4, v126
	v_and_b32_e32 v190, 0xf0f0f0f, v129
	v_lshrrev_b32_e32 v129, 4, v129
	v_dot4c_i32_i8_e32 v27, v161, v5
	v_and_b32_e32 v60, 0xf0f0f0f, v61
	v_and_b32_e32 v61, 0xf0f0f0f, v62
	v_and_b32_e32 v62, 0xf0f0f0f, v63
	v_and_b32_e32 v63, 0xf0f0f0f, v104
	v_and_b32_e32 v104, 0xf0f0f0f, v107
	v_dot4c_i32_i8_e32 v31, v169, v5
	v_and_b32_e32 v107, 0xf0f0f0f, v110
	v_and_b32_e32 v110, 0xf0f0f0f, v113
	v_and_b32_e32 v113, 0xf0f0f0f, v116
	v_and_b32_e32 v116, 0xf0f0f0f, v119
	v_and_b32_e32 v119, 0xf0f0f0f, v122
	v_dot4c_i32_i8_e32 v39, v185, v5
	v_and_b32_e32 v122, 0xf0f0f0f, v125
	v_and_b32_e32 v125, 0xf0f0f0f, v128
	v_dot4c_i32_i8_e32 v25, v158, v7
	v_dot4c_i32_i8_e32 v28, v59, v6
	v_dot4c_i32_i8_e32 v32, v105, v6
	v_dot4c_i32_i8_e32 v40, v121, v6
	v_dot4c_i32_i8_e32 v26, v56, v8
	v_and_b32_e32 v188, 0xf0f0f0f, v127
	v_lshrrev_b32_e32 v127, 4, v127
	v_and_b32_e32 v191, 0xf0f0f0f, v130
	v_lshrrev_b32_e32 v130, 4, v130
	s_waitcnt vmcnt(5)
	v_and_b32_e32 v193, 0xf0f0f0f, v132
	v_lshrrev_b32_e32 v132, 4, v132
	v_dot4c_i32_i8_e32 v29, v165, v5
	v_and_b32_e32 v108, 0xf0f0f0f, v111
	v_dot4c_i32_i8_e32 v33, v173, v5
	v_and_b32_e32 v111, 0xf0f0f0f, v114
	v_and_b32_e32 v114, 0xf0f0f0f, v117
	v_and_b32_e32 v117, 0xf0f0f0f, v120
	v_and_b32_e32 v120, 0xf0f0f0f, v123
	v_and_b32_e32 v123, 0xf0f0f0f, v126
	v_dot4c_i32_i8_e32 v41, v189, v5
	v_and_b32_e32 v126, 0xf0f0f0f, v129
	v_dot4c_i32_i8_e32 v27, v162, v7
	v_dot4c_i32_i8_e32 v30, v63, v6
	v_dot4c_i32_i8_e32 v31, v170, v7
	v_dot4c_i32_i8_e32 v34, v109, v6
	v_dot4c_i32_i8_e32 v39, v186, v7
	v_dot4c_i32_i8_e32 v42, v125, v6
	v_dot4c_i32_i8_e32 v25, v159, v9
	v_dot4c_i32_i8_e32 v28, v60, v8
	v_dot4c_i32_i8_e32 v32, v106, v8
	v_dot4c_i32_i8_e32 v40, v122, v8
	v_dot4c_i32_i8_e32 v26, v57, v10
	v_and_b32_e32 v192, 0xf0f0f0f, v131
	v_lshrrev_b32_e32 v131, 4, v131
	v_and_b32_e32 v194, 0xf0f0f0f, v133
	v_lshrrev_b32_e32 v133, 4, v133
	v_and_b32_e32 v124, 0xf0f0f0f, v127
	v_and_b32_e32 v127, 0xf0f0f0f, v130
	v_and_b32_e32 v129, 0xf0f0f0f, v132
	v_dot4c_i32_i8_e32 v29, v166, v7
	v_dot4c_i32_i8_e32 v33, v174, v7
	v_dot4c_i32_i8_e32 v41, v190, v7
	v_dot4c_i32_i8_e32 v27, v163, v9
	v_dot4c_i32_i8_e32 v30, v87, v8
	v_dot4c_i32_i8_e32 v31, v171, v9
	v_dot4c_i32_i8_e32 v34, v110, v8
	v_dot4c_i32_i8_e32 v39, v187, v9
	v_dot4c_i32_i8_e32 v42, v126, v8
	v_dot4c_i32_i8_e32 v25, v160, v11
	v_dot4c_i32_i8_e32 v28, v61, v10
	v_dot4c_i32_i8_e32 v32, v107, v10
	v_dot4c_i32_i8_e32 v40, v123, v10
	v_dot4c_i32_i8_e32 v26, v58, v12
	v_and_b32_e32 v195, 0xf0f0f0f, v134
	v_lshrrev_b32_e32 v134, 4, v134
	s_waitcnt vmcnt(4)
	v_and_b32_e32 v197, 0xf0f0f0f, v136
	v_lshrrev_b32_e32 v136, 4, v136
	v_and_b32_e32 v128, 0xf0f0f0f, v131
	v_dot4c_i32_i8_e32 v43, v193, v5
	v_and_b32_e32 v130, 0xf0f0f0f, v133
	v_dot4c_i32_i8_e32 v44, v129, v6
	v_dot4c_i32_i8_e32 v29, v167, v9
	v_dot4c_i32_i8_e32 v33, v175, v9
	v_dot4c_i32_i8_e32 v41, v191, v9
	v_dot4c_i32_i8_e32 v27, v164, v11
	v_dot4c_i32_i8_e32 v30, v103, v10
	v_dot4c_i32_i8_e32 v31, v172, v11
	v_dot4c_i32_i8_e32 v34, v111, v10
	v_dot4c_i32_i8_e32 v39, v188, v11
	v_dot4c_i32_i8_e32 v42, v127, v10
	v_dot4c_i32_i8_e32 v28, v62, v12
	v_dot4c_i32_i8_e32 v32, v108, v12
	v_dot4c_i32_i8_e32 v40, v124, v12
	v_add_u32_e32 v25, v26, v25
	v_and_b32_e32 v196, 0xf0f0f0f, v135
	v_lshrrev_b32_e32 v135, 4, v135
	v_and_b32_e32 v198, 0xf0f0f0f, v137
	v_lshrrev_b32_e32 v137, 4, v137
	v_dot4c_i32_i8_e32 v35, v177, v5
	v_and_b32_e32 v131, 0xf0f0f0f, v134
	v_and_b32_e32 v133, 0xf0f0f0f, v136
	v_dot4c_i32_i8_e32 v36, v113, v6
	v_dot4c_i32_i8_e32 v43, v194, v7
	v_dot4c_i32_i8_e32 v44, v130, v8
	v_dot4c_i32_i8_e32 v29, v168, v11
	v_dot4c_i32_i8_e32 v33, v176, v11
	v_dot4c_i32_i8_e32 v41, v192, v11
	v_dot4c_i32_i8_e32 v30, v104, v12
	v_dot4c_i32_i8_e32 v34, v112, v12
	v_dot4c_i32_i8_e32 v42, v128, v12
	v_add_u32_e32 v26, v28, v27
	v_add_u32_e32 v28, v32, v31
	v_add_u32_e32 v32, v40, v39
	v_and_b32_e32 v199, 0xf0f0f0f, v138
	v_lshrrev_b32_e32 v138, 4, v138
	s_waitcnt vmcnt(3)
; __device__ void peer_phase(const Params& p) {
;     ...
;         for (int u = 0; u < 16; ++u) {
;           const u32 w[4] = {d[u].x, d[u].y, d[u].z, d[u].w};
;           int s0 = 0, s1 = 0;
; #pragma unroll
;           for (int k = 0; k < 4; ++k) {
;             s0 = __builtin_amdgcn_sdot4((int)(w[k] & 0x0F0F0F0Fu), hq[2 * k], s0, false);
;             s1 = __builtin_amdgcn_sdot4((int)((w[k] >> 4) & 0x0F0F0F0Fu), hq[2 * k + 1], s1, false);
;           }
;           const int sI = wave_sum_i(s0 + s1);
	v_and_b32_e32 v201, 0xf0f0f0f, v140
	v_lshrrev_b32_e32 v140, 4, v140
	v_dot4c_i32_i8_e32 v37, v181, v5
	v_and_b32_e32 v132, 0xf0f0f0f, v135
	v_dot4c_i32_i8_e32 v45, v197, v5
	v_and_b32_e32 v134, 0xf0f0f0f, v137
	v_dot4c_i32_i8_e32 v35, v178, v7
	v_dot4c_i32_i8_e32 v38, v117, v6
	v_dot4c_i32_i8_e32 v46, v133, v6
	v_dot4c_i32_i8_e32 v36, v114, v8
	v_dot4c_i32_i8_e32 v43, v195, v9
	v_dot4c_i32_i8_e32 v44, v131, v10
	v_add_u32_e32 v27, v30, v29
	v_add_u32_e32 v29, v34, v33
	v_add_u32_e32 v33, v42, v41
	v_and_b32_e32 v200, 0xf0f0f0f, v139
	v_lshrrev_b32_e32 v139, 4, v139
	v_and_b32_e32 v202, 0xf0f0f0f, v141
	v_lshrrev_b32_e32 v141, 4, v141
	v_and_b32_e32 v135, 0xf0f0f0f, v138
	v_and_b32_e32 v137, 0xf0f0f0f, v140
	v_dot4c_i32_i8_e32 v37, v182, v7
	v_dot4c_i32_i8_e32 v45, v198, v7
	v_dot4c_i32_i8_e32 v35, v179, v9
	v_dot4c_i32_i8_e32 v38, v118, v8
	v_dot4c_i32_i8_e32 v46, v134, v8
	v_dot4c_i32_i8_e32 v36, v115, v10
	v_dot4c_i32_i8_e32 v43, v196, v11
	v_dot4c_i32_i8_e32 v44, v132, v12
	v_and_b32_e32 v203, 0xf0f0f0f, v142
	v_lshrrev_b32_e32 v142, 4, v142
	s_waitcnt vmcnt(2)
	v_and_b32_e32 v205, 0xf0f0f0f, v144
	v_lshrrev_b32_e32 v144, 4, v144
	v_and_b32_e32 v136, 0xf0f0f0f, v139
	v_dot4c_i32_i8_e32 v47, v201, v5
	v_and_b32_e32 v138, 0xf0f0f0f, v141
	v_dot4c_i32_i8_e32 v48, v137, v6
	v_dot4c_i32_i8_e32 v37, v183, v9
	v_dot4c_i32_i8_e32 v45, v199, v9
	v_dot4c_i32_i8_e32 v35, v180, v11
	v_dot4c_i32_i8_e32 v38, v119, v10
	v_dot4c_i32_i8_e32 v46, v135, v10
	v_dot4c_i32_i8_e32 v36, v116, v12
	v_add_u32_e32 v34, v44, v43
	v_and_b32_e32 v204, 0xf0f0f0f, v143
	v_lshrrev_b32_e32 v143, 4, v143
	v_and_b32_e32 v206, 0xf0f0f0f, v145
	v_lshrrev_b32_e32 v145, 4, v145
	v_and_b32_e32 v139, 0xf0f0f0f, v142
	v_and_b32_e32 v141, 0xf0f0f0f, v144
	v_dot4c_i32_i8_e32 v47, v202, v7
	v_dot4c_i32_i8_e32 v48, v138, v8
	v_dot4c_i32_i8_e32 v37, v184, v11
	v_dot4c_i32_i8_e32 v45, v200, v11
	v_dot4c_i32_i8_e32 v38, v120, v12
	v_dot4c_i32_i8_e32 v46, v136, v12
	v_add_u32_e32 v30, v36, v35
	v_and_b32_e32 v207, 0xf0f0f0f, v146
	v_lshrrev_b32_e32 v146, 4, v146
	s_waitcnt vmcnt(1)
	v_and_b32_e32 v209, 0xf0f0f0f, v148
	v_lshrrev_b32_e32 v148, 4, v148
	v_and_b32_e32 v140, 0xf0f0f0f, v143
	v_dot4c_i32_i8_e32 v49, v205, v5
	v_and_b32_e32 v142, 0xf0f0f0f, v145
	v_dot4c_i32_i8_e32 v50, v141, v6
	v_dot4c_i32_i8_e32 v47, v203, v9
	v_dot4c_i32_i8_e32 v48, v139, v10
	v_add_u32_e32 v31, v38, v37
	v_add_u32_e32 v35, v46, v45
	v_and_b32_e32 v208, 0xf0f0f0f, v147
	v_lshrrev_b32_e32 v147, 4, v147
	v_and_b32_e32 v210, 0xf0f0f0f, v149
	v_lshrrev_b32_e32 v149, 4, v149
	v_and_b32_e32 v143, 0xf0f0f0f, v146
	v_and_b32_e32 v145, 0xf0f0f0f, v148
	v_dot4c_i32_i8_e32 v49, v206, v7
	v_dot4c_i32_i8_e32 v50, v142, v8
	v_dot4c_i32_i8_e32 v47, v204, v11
	v_dot4c_i32_i8_e32 v48, v140, v12
	v_and_b32_e32 v211, 0xf0f0f0f, v150
	v_lshrrev_b32_e32 v150, 4, v150
	s_waitcnt vmcnt(0)
; __device__ void peer_phase(const Params& p) {
;     ...
;           const int sI = wave_sum_i(s0 + s1);
;           if (lane == e + u) acti = sI;
;         }
;       }
;       const float act = ((float)acti - 7.5f * (float)hsum) * sh * (hf == 0 ? ds0 : ds1);
;       gg[hf] *= 0.5f * act * (1.f + erff(act * 0.70710678118654752f)) * (hf == 0 ? us0 : us1);
	v_and_b32_e32 v213, 0xf0f0f0f, v152
	v_lshrrev_b32_e32 v152, 4, v152
	v_and_b32_e32 v144, 0xf0f0f0f, v147
	v_dot4c_i32_i8_e32 v51, v209, v5
	v_and_b32_e32 v146, 0xf0f0f0f, v149
	v_dot4c_i32_i8_e32 v77, v145, v6
	v_dot4c_i32_i8_e32 v49, v207, v9
	v_dot4c_i32_i8_e32 v50, v143, v10
	v_add_u32_e32 v36, v48, v47
	v_and_b32_e32 v212, 0xf0f0f0f, v151
	v_lshrrev_b32_e32 v151, 4, v151
	v_and_b32_e32 v214, 0xf0f0f0f, v153
	v_lshrrev_b32_e32 v153, 4, v153
	v_and_b32_e32 v147, 0xf0f0f0f, v150
	v_and_b32_e32 v149, 0xf0f0f0f, v152
	v_dot4c_i32_i8_e32 v51, v210, v7
	v_dot4c_i32_i8_e32 v77, v146, v8
	v_dot4c_i32_i8_e32 v49, v208, v11
	v_dot4c_i32_i8_e32 v50, v144, v12
	v_and_b32_e32 v215, 0xf0f0f0f, v154
	v_lshrrev_b32_e32 v154, 4, v154
	v_and_b32_e32 v148, 0xf0f0f0f, v151
	v_dot4c_i32_i8_e32 v79, v213, v5
	v_and_b32_e32 v150, 0xf0f0f0f, v153
	v_dot4c_i32_i8_e32 v83, v149, v6
	v_dot4c_i32_i8_e32 v51, v211, v9
	v_dot4c_i32_i8_e32 v77, v147, v10
	v_add_u32_e32 v37, v50, v49
	v_and_b32_e32 v216, 0xf0f0f0f, v155
	v_lshrrev_b32_e32 v155, 4, v155
	v_and_b32_e32 v151, 0xf0f0f0f, v154
	v_dot4c_i32_i8_e32 v79, v214, v7
	v_dot4c_i32_i8_e32 v83, v150, v8
	v_dot4c_i32_i8_e32 v51, v212, v11
	v_dot4c_i32_i8_e32 v77, v148, v12
	v_and_b32_e32 v152, 0xf0f0f0f, v155
	v_dot4c_i32_i8_e32 v79, v215, v9
	v_dot4c_i32_i8_e32 v83, v151, v10
	v_add_u32_e32 v38, v77, v51
	v_dot4c_i32_i8_e32 v79, v216, v11
	v_dot4c_i32_i8_e32 v83, v152, v12
	s_nop 2
	v_add_u32_e32 v39, v83, v79
	s_mov_b32 s0, s4
	s_add_i32 s44, s4, 16
	s_cmp_lt_u32 s0, 48
	s_mov_b32 s4, s44
	s_nop 1
	v_add_u32_dpp v40, v23, v23 row_mirror row_mask:0xf bank_mask:0x3
	v_add_u32_dpp v40, v32, v32 row_mirror row_mask:0xf bank_mask:0xc
	v_add_u32_dpp v41, v25, v25 row_mirror row_mask:0xf bank_mask:0x3
	v_add_u32_dpp v41, v33, v33 row_mirror row_mask:0xf bank_mask:0xc
	v_add_u32_dpp v42, v26, v26 row_mirror row_mask:0xf bank_mask:0x3
	v_add_u32_dpp v42, v34, v34 row_mirror row_mask:0xf bank_mask:0xc
	v_add_u32_dpp v43, v27, v27 row_mirror row_mask:0xf bank_mask:0x3
	v_add_u32_dpp v43, v35, v35 row_mirror row_mask:0xf bank_mask:0xc
	v_add_u32_dpp v44, v28, v28 row_mirror row_mask:0xf bank_mask:0x3
	v_add_u32_dpp v44, v36, v36 row_mirror row_mask:0xf bank_mask:0xc
	v_add_u32_dpp v45, v29, v29 row_mirror row_mask:0xf bank_mask:0x3
	v_add_u32_dpp v45, v37, v37 row_mirror row_mask:0xf bank_mask:0xc
	v_add_u32_dpp v46, v30, v30 row_mirror row_mask:0xf bank_mask:0x3
	v_add_u32_dpp v46, v38, v38 row_mirror row_mask:0xf bank_mask:0xc
	v_add_u32_dpp v47, v31, v31 row_mirror row_mask:0xf bank_mask:0x3
	v_add_u32_dpp v47, v39, v39 row_mirror row_mask:0xf bank_mask:0xc
	v_add_u32_dpp v48, v40, v40 row_half_mirror row_mask:0xf bank_mask:0x5
	v_add_u32_dpp v48, v44, v44 row_half_mirror row_mask:0xf bank_mask:0xa
	v_add_u32_dpp v49, v41, v41 row_half_mirror row_mask:0xf bank_mask:0x5
	v_add_u32_dpp v49, v45, v45 row_half_mirror row_mask:0xf bank_mask:0xa
	v_add_u32_dpp v50, v42, v42 row_half_mirror row_mask:0xf bank_mask:0x5
	v_add_u32_dpp v50, v46, v46 row_half_mirror row_mask:0xf bank_mask:0xa
	v_add_u32_dpp v51, v43, v43 row_half_mirror row_mask:0xf bank_mask:0x5
	v_add_u32_dpp v51, v47, v47 row_half_mirror row_mask:0xf bank_mask:0xa
	v_add_u32_dpp v48, v48, v48 quad_perm:[1,0,3,2] row_mask:0xf bank_mask:0xf
	v_add_u32_dpp v49, v49, v49 quad_perm:[1,0,3,2] row_mask:0xf bank_mask:0xf
	v_add_u32_dpp v50, v50, v50 quad_perm:[1,0,3,2] row_mask:0xf bank_mask:0xf
	v_add_u32_dpp v51, v51, v51 quad_perm:[1,0,3,2] row_mask:0xf bank_mask:0xf
	v_add_u32_dpp v48, v48, v48 quad_perm:[2,3,0,1] row_mask:0xf bank_mask:0xf
	v_add_u32_dpp v49, v49, v49 quad_perm:[2,3,0,1] row_mask:0xf bank_mask:0xf
	v_add_u32_dpp v50, v50, v50 quad_perm:[2,3,0,1] row_mask:0xf bank_mask:0xf
	v_add_u32_dpp v51, v51, v51 quad_perm:[2,3,0,1] row_mask:0xf bank_mask:0xf
	s_mov_b32 vcc_lo, 0x22222222
	s_mov_b32 vcc_hi, 0x22222222
	s_nop 1
	v_cndmask_b32_e32 v48, v48, v49, vcc
	s_mov_b32 vcc_lo, 0x44444444
	s_mov_b32 vcc_hi, 0x44444444
	s_nop 1
	v_cndmask_b32_e32 v48, v48, v50, vcc
	s_mov_b32 vcc_lo, 0x88888888
	s_mov_b32 vcc_hi, 0x88888888
	s_nop 1
	v_cndmask_b32_e32 v48, v48, v51, vcc
	ds_bpermute_b32 v52, v90, v48
	v_and_b32_e32 v49, 48, v88
	v_cmp_eq_u32_e32 vcc, s0, v49
	s_waitcnt lgkmcnt(0)
	v_add_u32_e32 v48, v52, v48
	ds_bpermute_b32 v52, v89, v48
	s_waitcnt lgkmcnt(0)
	v_add_u32_e32 v48, v52, v48
	s_nop 1
	v_cndmask_b32_e32 v22, v22, v48, vcc
	s_cbranch_scc1 .LBB0_857
	v_cvt_f32_i32_e32 v5, v22
	v_sub_f32_e32 v5, v5, v21
	v_mul_f32_e32 v5, v20, v5
	v_mul_f32_e32 v5, v3, v5
	v_mul_f32_e32 v3, 0x3f3504f3, v5
	v_cmp_nlt_f32_e64 s[0:1], |v3|, 1.0
	s_and_saveexec_b64 s[4:5], s[0:1]
	s_xor_b64 s[0:1], exec, s[4:5]
	s_cbranch_execz .LBB0_860
	v_fma_f32 v6, |v3|, s12, v100
	v_fma_f32 v6, |v3|, v6, s13
	v_fma_f32 v6, |v3|, v6, s14
	v_fma_f32 v6, |v3|, v6, s15
	v_fma_f32 v6, |v3|, v6, s16
	v_fma_f32 v6, |v3|, v6, s17
	v_fma_f32 v6, |v3|, v6, |v3|
	v_mul_f32_e32 v7, 0xbfb8aa3b, v6
	v_fma_f32 v8, v6, s18, -v7
	v_rndne_f32_e32 v9, v7
	v_fmac_f32_e32 v8, 0xb2a5705f, v6
	v_sub_f32_e32 v7, v7, v9
	v_add_f32_e32 v7, v7, v8
	v_cvt_i32_f32_e32 v8, v9
	v_exp_f32_e32 v7, v7
	v_cmp_nlt_f32_e32 vcc, s19, v6
	v_ldexp_f32 v7, v7, v8
	s_nop 0
	v_cndmask_b32_e32 v7, 0, v7, vcc
	v_cmp_ngt_f32_e32 vcc, s20, v6
	s_nop 1
	v_cndmask_b32_e32 v6, v101, v7, vcc
	v_sub_f32_e32 v6, 1.0, v6
